# P1b->H1 seam split-phase: arrive after each WG's 4th P1b unit (q,f,i column rounds), wait at H1 start behind the gate-tile round
# speedup vs baseline: 1.0085x; 1.0085x over previous
.LBB0_112:
	s_cmp_lt_i32 s78, 2
	s_cselect_b64 s[2:3], -1, 0
	s_add_u32 s94, s76, 0x3000000
	v_readlane_b32 s4, v246, 20
	s_addc_u32 s95, s77, 0
	v_readlane_b32 s18, v246, 34
	v_readlane_b32 s6, v246, 22
	v_readlane_b32 s7, v246, 23
	v_readlane_b32 s19, v246, 35
	s_add_u32 s88, s18, 0x2000000
	s_addc_u32 s89, s19, 0
	s_and_b64 s[6:7], s[2:3], s[0:1]
	s_andn2_b64 vcc, exec, s[6:7]
	v_readlane_b32 s5, v246, 21
	v_readlane_b32 s8, v246, 24
	v_readlane_b32 s9, v246, 25
	v_readlane_b32 s10, v246, 26
	v_readlane_b32 s11, v246, 27
	v_readlane_b32 s12, v246, 28
	v_readlane_b32 s13, v246, 29
	v_readlane_b32 s14, v246, 30
	v_readlane_b32 s15, v246, 31
	v_readlane_b32 s16, v246, 32
	v_readlane_b32 s17, v246, 33
	s_cbranch_vccnz .LBB0_227
	s_mov_b32 s87, 0
	s_cmpk_lt_i32 s74, 0x500
	s_cselect_b64 s[0:1], -1, 0
	s_cmpk_gt_i32 s74, 0x4ff
	v_readfirstlane_b32 s12, v171
	s_cbranch_scc1 .LBB0_115
	s_ashr_i32 s2, s74, 31
	s_lshr_b32 s2, s2, 29
	s_add_i32 s2, s74, s2
	s_ashr_i32 s3, s2, 3
	s_and_b32 s2, s2, -8
	s_sub_i32 s2, s74, s2
	s_cmp_lt_i32 s2, 0
	s_movk_i32 s4, 0xa1
	s_cselect_b32 s4, s4, 0xa0
	s_mul_i32 s2, s2, s4
	s_add_i32 s2, s2, s3
	s_mul_hi_i32 s3, s2, 0x66666667
	s_lshr_b32 s4, s3, 31
	s_ashr_i32 s3, s3, 6
	s_add_i32 s3, s3, s4
	s_lshl_b32 s4, s3, 3
	s_mulk_i32 s3, 0xa0
	s_sub_i32 s2, s2, s3
	s_sext_i32_i16 s3, s2
	s_bfe_u32 s3, s3, 0x3001c
	s_add_i32 s3, s2, s3
	s_sext_i32_i16 s5, s3
	s_and_b32 s3, s3, 0xfff8
	s_sub_i32 s2, s2, s3
	s_sext_i32_i16 s2, s2
	s_add_i32 s4, s4, s2
	s_ashr_i32 s24, s5, 3

.LBB0_223:
	v_cvt_pk_bf16_f32 v0, v8, v9
	v_cvt_pk_bf16_f32 v1, v10, v11
	v_cvt_pk_bf16_f32 v2, v12, v13
	v_cvt_pk_bf16_f32 v3, v14, v15
	s_andn2_b64 vcc, exec, s[0:1]
	s_mov_b64 s[0:1], -1
	global_store_dwordx4 v[24:25], v[0:3], off offset:256
	s_mov_b64 s[72:73], vcc
	s_add_i32 s87, s87, 1
	s_cmp_eq_u32 s87, 4
	s_cbranch_scc0 .Ldf1_skip
	s_and_b64 vcc, exec, s[92:93]
	s_cbranch_vccz .Ldf1_skip
	s_waitcnt vmcnt(0)
	s_barrier
	s_mov_b32 s100, 1
	v_cmp_eq_u32_e32 vcc, 0, v171
	s_and_saveexec_b64 s[98:99], vcc
	s_cbranch_execz .Ldf1_arr
	v_mov_b32_e32 v247, 0x20000
	ds_read_b32 v248, v247
	v_readlane_b32 s96, v246, 1
	v_readlane_b32 s97, v246, 2
	v_readlane_b32 s101, v246, 3
	s_lshl_b32 s101, s101, 2
	s_addk_i32 s101, 0x3a00
	v_mov_b32_e32 v249, s101
	v_mov_b32_e32 v250, 1
	s_nop 2
	global_atomic_add v251, v249, v250, s[96:97] sc0
	s_waitcnt vmcnt(0) lgkmcnt(0)
	v_add_u32_e32 v251, 1, v251
	v_cmp_eq_u32_e32 vcc, v251, v248
	s_cbranch_vccz .Ldf1_arr
	buffer_wbl2 sc1
	s_waitcnt vmcnt(0)
	v_mov_b32_e32 v249, 0x3a40
	global_atomic_add v249, v250, s[96:97]

.Ldf1_skip:
	s_mov_b64 vcc, s[72:73]
	s_cbranch_vccnz .LBB0_120
	s_andn2_b64 vcc, exec, s[8:9]
	s_cbranch_vccnz .LBB0_119
	s_barrier
	s_branch .LBB0_119

.LBB0_227:
	s_cmp_gt_i32 s79, 2
	s_cselect_b64 s[0:1], -1, 0
	s_and_b64 s[2:3], s[6:7], s[0:1]
	s_andn2_b64 vcc, exec, s[2:3]
	s_cbranch_vccnz .LBB0_277
	s_cmp_eq_u32 s100, 1
	s_cbranch_scc0 .Ldf1_orig
	s_cmp_eq_u32 s100, 1
	s_cbranch_scc0 .Ldf1_wd
	s_mov_b32 s100, 0
	v_cmp_eq_u32_e64 s[98:99], 0, v171
	s_nop 1
	s_and_saveexec_b64 s[98:99], s[98:99]
	s_cbranch_execz .Ldf1_wj
	v_mov_b32_e32 v247, 0x20004
	ds_read_b32 v248, v247
	v_readlane_b32 s96, v246, 1
	v_readlane_b32 s97, v246, 2
	v_mov_b32_e32 v249, 0x3a40
	s_mov_b32 s90, 0
	s_waitcnt lgkmcnt(0)
	v_readfirstlane_b32 s101, v248
	s_nop 3

.Ldf1_wd:
	s_branch .LBB0_277
.Ldf1_orig:
	s_waitcnt vmcnt(0)
	v_cmp_eq_u32_e32 vcc, 0, v171
	s_waitcnt vmcnt(0)
	s_barrier
	s_and_saveexec_b64 s[2:3], vcc
	s_cbranch_execz .LBB0_276
	s_add_i32 s4, 0, 0x20000
	v_mov_b32_e32 v0, s4
	s_waitcnt vmcnt(0) expcnt(0) lgkmcnt(0)
	ds_read_b32 v2, v0
	s_add_i32 s4, 0, 0x20004
	v_mov_b32_e32 v0, s4
	ds_read_b32 v0, v0
	s_waitcnt lgkmcnt(1)
	v_cmp_ne_u32_e32 vcc, 0, v2
	s_cbranch_vccnz .LBB0_244
	v_readlane_b32 s4, v246, 0
	s_mul_i32 s33, s53, s4
	s_add_u32 s4, s76, 0x280200
	s_addc_u32 s5, s77, 0
	s_add_u32 s6, s76, 0x280400
	s_addc_u32 s7, s77, 0
	s_add_u32 s8, s76, 0x280500
	s_addc_u32 s9, s77, 0
	s_add_u32 s10, s76, 0x280600
	s_addc_u32 s11, s77, 0
	s_add_u32 s12, s76, 0x280700
	s_addc_u32 s13, s77, 0
	s_add_u32 s14, s76, 0x280800
	s_addc_u32 s15, s77, 0
	s_add_u32 s16, s76, 0x280900
	s_addc_u32 s17, s77, 0
	s_add_u32 s18, s76, 0x280a00
	s_addc_u32 s19, s77, 0
	s_add_u32 s20, s76, 0x280b00
	s_addc_u32 s21, s77, 0
	s_add_u32 s22, s76, 0x280c00
	s_addc_u32 s23, s77, 0
	s_add_u32 s24, s76, 0x280d00
	s_addc_u32 s25, s77, 0
	s_add_u32 s26, s76, 0x280e00
	s_addc_u32 s27, s77, 0
	s_add_u32 s28, s76, 0x280f00
	s_addc_u32 s29, s77, 0
	s_add_u32 s30, s76, 0x281000
	s_addc_u32 s31, s77, 0
	s_add_u32 s34, s76, 0x281100
	s_addc_u32 s35, s77, 0
	s_add_u32 s36, s76, 0x281200
	s_addc_u32 s37, s77, 0
	s_add_u32 s38, s76, 0x281300
	s_mul_i32 s33, s33, s52
	s_addc_u32 s39, s77, 0
	s_mov_b32 s46, 1
	v_mov_b32_e32 v16, 0
	s_branch .LBB0_232
